# scan LDS layout: per-row v values for 4 steps and look-ahead scalars for 4 pairs packed contiguously so one ds_read_b128 replaces two ds_read2_b32
# speedup vs baseline: 1.0269x; 1.0050x over previous
.LBB0_485:
	s_or_saveexec_b64 s[6:7], s[6:7]
	s_and_b32 s37, s8, 48
	s_xor_b64 exec, exec, s[6:7]
	s_cbranch_execz .LBB0_493
	s_add_u32 s14, s16, 0xc500000
	v_add_u32_e32 v3, 0xffffff00, v0
	s_waitcnt vmcnt(5)
	v_mov_b32_e32 v11, 0
	s_addc_u32 s15, s17, 0
	s_lshl_b64 s[8:9], s[10:11], 12
	v_lshrrev_b32_e32 v10, 4, v3
	v_mov_b32_e32 v7, v11
	s_lshl_b32 s33, s36, 6
	v_lshlrev_b32_e32 v2, 2, v3
	v_lshl_add_u64 v[4:5], s[8:9], 0, v[10:11]
	s_waitcnt vmcnt(0)
	v_lshl_add_u64 v[16:17], s[8:9], 0, v[6:7]
	v_and_or_b32 v8, v2, 60, s33
	s_add_u32 s34, s16, 0xd500000
	v_lshlrev_b64 v[4:5], 8, v[4:5]
	v_lshlrev_b64 v[22:23], 8, v[16:17]
	s_addc_u32 s35, s17, 0
	v_or_b32_e32 v4, v4, v8
	v_or_b32_e32 v22, v22, v8
	v_lshl_add_u64 v[12:13], v[4:5], 2, s[14:15]
	v_lshlrev_b64 v[4:5], 1, v[4:5]
	v_lshl_add_u64 v[24:25], v[22:23], 2, s[14:15]
	s_add_u32 s14, s16, 0xdd00000
	v_lshl_add_u64 v[20:21], s[34:35], 0, v[4:5]
	s_addc_u32 s15, s17, 0
	global_load_dwordx4 v[12:15], v[12:13], off
	s_nop 0
	global_load_dwordx4 v[16:19], v[24:25], off
	global_load_dwordx2 v[26:27], v[20:21], off
	v_lshl_add_u64 v[20:21], s[14:15], 0, v[4:5]
	global_load_dwordx2 v[24:25], v[20:21], off
	v_lshlrev_b64 v[20:21], 1, v[22:23]
	v_lshl_add_u64 v[22:23], s[34:35], 0, v[20:21]
	global_load_dwordx2 v[28:29], v[22:23], off
	v_lshl_add_u64 v[22:23], s[14:15], 0, v[20:21]
	s_add_u32 s14, s16, 0xe500000
	s_addc_u32 s15, s17, 0
	global_load_dwordx2 v[30:31], v[22:23], off
	v_lshl_add_u64 v[22:23], s[14:15], 0, v[4:5]
	global_load_dwordx2 v[32:33], v[22:23], off
	v_lshl_add_u64 v[22:23], s[14:15], 0, v[20:21]
	s_add_u32 s14, s16, 0xed00000
	s_addc_u32 s15, s17, 0
	v_lshl_add_u64 v[4:5], s[14:15], 0, v[4:5]
	global_load_dwordx2 v[34:35], v[22:23], off
	v_lshl_add_u64 v[20:21], s[14:15], 0, v[20:21]
	global_load_dwordx2 v[4:5], v[4:5], off
	s_movk_i32 s14, 0x50
	global_load_dwordx2 v[36:37], v[20:21], off
	v_mul_lo_u32 v20, v0, s14
	v_add_u32_e32 v21, 0xffffb000, v20
	v_add_u32_e32 v38, 0, v21
	v_add_u32_e32 v9, 0, v20
	s_movk_i32 s14, 0x7f
	v_cmp_lt_u32_e32 vcc, s14, v3
	s_waitcnt vmcnt(9)
	ds_write_b128 v38, v[12:15]
	s_waitcnt vmcnt(8)
	ds_write_b128 v9, v[16:19]
	s_waitcnt vmcnt(7)
	v_lshlrev_b32_e32 v12, 16, v26
	v_and_b32_e32 v13, 0xffff0000, v26
	v_lshlrev_b32_e32 v14, 16, v27
	v_and_b32_e32 v15, 0xffff0000, v27
	s_waitcnt vmcnt(6)
	v_lshlrev_b32_e32 v16, 16, v24
	v_and_b32_e32 v17, 0xffff0000, v24
	v_lshlrev_b32_e32 v18, 16, v25
	v_and_b32_e32 v19, 0xffff0000, v25
	s_waitcnt vmcnt(5)
	v_lshlrev_b32_e32 v22, 16, v28
	v_and_b32_e32 v23, 0xffff0000, v28
	v_lshlrev_b32_e32 v24, 16, v29
	v_and_b32_e32 v25, 0xffff0000, v29
	s_waitcnt vmcnt(4)
	v_lshlrev_b32_e32 v26, 16, v30
	v_and_b32_e32 v27, 0xffff0000, v30
	v_lshlrev_b32_e32 v28, 16, v31
	v_and_b32_e32 v29, 0xffff0000, v31
	ds_write_b128 v38, v[12:15] offset:16
	ds_write_b128 v38, v[16:19] offset:32
	ds_write_b128 v9, v[22:25] offset:16
	ds_write_b128 v9, v[26:29] offset:32
	s_waitcnt vmcnt(3)
	v_lshlrev_b32_e32 v12, 16, v32
	v_and_b32_e32 v13, 0xffff0000, v32
	v_lshlrev_b32_e32 v14, 16, v33
	v_and_b32_e32 v15, 0xffff0000, v33
	s_waitcnt vmcnt(2)
	v_lshlrev_b32_e32 v16, 16, v34
	v_and_b32_e32 v17, 0xffff0000, v34
	v_lshlrev_b32_e32 v18, 16, v35
	v_and_b32_e32 v19, 0xffff0000, v35
	ds_write_b128 v38, v[12:15] offset:48
	ds_write_b128 v9, v[16:19] offset:48
	s_waitcnt vmcnt(1)
	v_lshlrev_b32_e32 v12, 16, v4
	v_and_b32_e32 v13, 0xffff0000, v4
	v_lshlrev_b32_e32 v14, 16, v5
	v_and_b32_e32 v15, 0xffff0000, v5
	s_waitcnt vmcnt(0)
	v_lshlrev_b32_e32 v16, 16, v36
	v_and_b32_e32 v17, 0xffff0000, v36
	v_lshlrev_b32_e32 v18, 16, v37
	v_and_b32_e32 v19, 0xffff0000, v37
	ds_write_b128 v38, v[12:15] offset:64
	ds_write_b128 v9, v[16:19] offset:64
	s_and_saveexec_b64 s[14:15], vcc
	s_xor_b64 s[14:15], exec, s[14:15]
	s_cbranch_execz .LBB0_490
	s_movk_i32 s34, 0xa0
	v_cmp_gt_u32_e32 vcc, s34, v3
	s_and_saveexec_b64 s[34:35], vcc
	s_cbranch_execz .LBB0_489
	v_add_u32_e32 v4, 0xfffffe80, v0
	v_mov_b32_e32 v5, 0
	v_lshl_add_u64 v[4:5], s[8:9], 0, v[4:5]
	s_mov_b32 s41, 0
	v_lshl_add_u64 v[4:5], v[4:5], 4, s[16:17]
	s_lshl_b32 s40, s36, 2
	v_lshl_add_u64 v[4:5], v[4:5], 0, s[40:41]
	v_add_co_u32_e32 v4, vcc, 0x780000, v4
	s_add_i32 s40, 0, 0x14000
	s_nop 0
	v_addc_co_u32_e32 v5, vcc, 0, v5, vcc
	global_load_dword v4, v[4:5], off
	v_add_u32_e32 v5, 0xfffffe80, v0
	v_and_b32_e32 v38, 1, v5
	v_xor_b32_e32 v38, 1, v38
	v_lshrrev_b32_e32 v5, 1, v5
	v_lshl_add_u32 v5, v38, 4, v5
	v_lshl_add_u32 v5, v5, 2, s40
	v_add_u32_e32 v5, 0x900, v5
	s_waitcnt vmcnt(0)
	ds_write_b32 v5, v4

.LBB0_490:
	s_andn2_saveexec_b64 s[14:15], s[14:15]
	s_cbranch_execz .LBB0_492
	v_lshrrev_b32_e32 v9, 2, v3
	v_or_b32_e32 v4, s8, v9
	v_mov_b32_e32 v5, s9
	v_lshlrev_b64 v[4:5], 9, v[4:5]
	v_lshl_add_u64 v[4:5], s[16:17], 0, v[4:5]
	s_lshl_b32 s8, s33, 1
	s_mov_b32 s9, 0
	v_lshl_add_u64 v[4:5], v[4:5], 0, s[8:9]
	s_lshl_b32 s8, s37, 1
	v_and_b32_e32 v14, 12, v2
	v_lshl_add_u64 v[4:5], v[4:5], 0, s[8:9]
	v_lshlrev_b32_e32 v12, 1, v14
	v_mov_b32_e32 v13, 0
	v_lshl_add_u64 v[4:5], v[4:5], 0, v[12:13]
	s_mov_b32 s8, 0x1d00000
	v_add_co_u32_e32 v4, vcc, s8, v4
	s_movk_i32 s8, 0x50
	s_nop 0
	v_addc_co_u32_e32 v5, vcc, 0, v5, vcc
	global_load_dwordx2 v[4:5], v[4:5], off
	s_add_i32 s9, 0, 0x14000
	v_lshlrev_b32_e32 v9, 2, v9
	v_mul_u32_u24_e32 v16, 0x90, v14
	s_waitcnt vmcnt(0)
	v_lshlrev_b32_e32 v12, 16, v4
	v_and_b32_e32 v13, 0xffff0000, v4
	v_lshlrev_b32_e32 v14, 16, v5
	v_and_b32_e32 v15, 0xffff0000, v5
	v_add3_u32 v4, s9, v9, v16
	ds_write_b32 v4, v12
	ds_write_b32 v4, v13 offset:144
	ds_write_b32 v4, v14 offset:288
	ds_write_b32 v4, v15 offset:432

.LBB0_493:
	s_or_b64 exec, exec, s[6:7]
	v_mov_b32_e32 v17, 0
	v_and_b32_e32 v18, 15, v0
	v_lshlrev_b32_e32 v23, 2, v1
	s_movk_i32 s14, 0x50
	s_waitcnt vmcnt(0)
	v_add_u32_e32 v16, 0xfffffe80, v0
	v_lshrrev_b32_e32 v0, 2, v3
	v_mov_b32_e32 v1, v17
	v_mad_u32_u24 v24, v18, s14, 0
	v_and_b32_e32 v29, 1, v16
	v_xor_b32_e32 v29, 1, v29
	v_lshrrev_b32_e32 v25, 1, v16
	v_lshl_add_u32 v25, v29, 4, v25
	v_lshlrev_b32_e32 v25, 2, v25
	v_add_u32_e32 v25, 0x8c0, v25
	v_lshlrev_b32_e32 v26, 2, v0
	s_lshl_b64 s[14:15], s[10:11], 21
	v_lshlrev_b64 v[0:1], 9, v[0:1]
	v_and_b32_e32 v27, 12, v2
	v_lshl_add_u64 v[0:1], s[14:15], 0, v[0:1]
	s_and_b32 s33, s72, 3
	v_lshlrev_b32_e32 v2, 1, v2
	v_lshl_or_b32 v0, s36, 7, v0
	s_lshl_b32 s33, s33, 5
	v_and_b32_e32 v2, 24, v2
	v_or3_b32 v0, v0, s33, v2
	v_lshl_add_u64 v[0:1], s[30:31], 0, v[0:1]
	s_mov_b64 s[34:35], 0x1d04000
	v_lshl_add_u64 v[0:1], v[0:1], 0, s[34:35]
	s_lshl_b64 s[34:35], s[10:11], 16
	s_lshl_b32 s33, s36, 2
	s_add_u32 s33, s30, s33
	s_addc_u32 s40, s31, 0
	s_add_u32 s34, s33, s34
	v_and_b32_e32 v22, 3, v6
	s_addc_u32 s35, s40, s35
	s_lshl_b64 s[10:11], s[10:11], 22
	v_lshlrev_b64 v[4:5], 10, v[6:7]
	v_lshlrev_b64 v[12:13], 2, v[8:9]
	v_lshlrev_b64 v[6:7], 9, v[6:7]
	v_lshlrev_b64 v[14:15], 1, v[8:9]
	v_lshlrev_b64 v[8:9], 10, v[10:11]
	v_lshlrev_b64 v[10:11], 9, v[10:11]
	v_and_b32_e32 v19, 12, v23
	v_lshl_add_u64 v[4:5], s[10:11], 0, v[4:5]
	v_lshl_add_u64 v[6:7], s[14:15], 0, v[6:7]
	v_lshl_add_u64 v[8:9], s[10:11], 0, v[8:9]
	v_lshl_add_u64 v[10:11], s[14:15], 0, v[10:11]
	s_movk_i32 s6, 0x7f
	s_movk_i32 s8, 0xa0
	v_lshl_add_u64 v[4:5], v[4:5], 0, v[12:13]
	v_lshl_add_u64 v[6:7], v[6:7], 0, v[14:15]
	v_lshl_add_u64 v[8:9], v[8:9], 0, v[12:13]
	v_lshl_add_u64 v[10:11], v[10:11], 0, v[14:15]
	v_lshl_or_b32 v12, v18, 10, s10
	v_add_u32_e32 v14, s37, v19
	v_cmp_lt_u32_e64 s[6:7], s6, v3
	v_cmp_gt_u32_e64 s[8:9], s8, v3
	v_lshl_add_u64 v[2:3], v[16:17], 4, s[34:35]
	s_mov_b64 s[34:35], 0x780200
	v_lshl_or_b32 v12, s36, 8, v12
	v_mov_b32_e32 v13, s11
	v_add_lshl_u32 v16, v14, v22, 2
	v_lshl_add_u64 v[2:3], v[2:3], 0, s[34:35]
	v_lshl_add_u64 v[4:5], s[30:31], 0, v[4:5]
	s_mov_b64 s[34:35], 0xc508000
	v_lshl_add_u64 v[8:9], s[30:31], 0, v[8:9]
	v_lshl_add_u64 v[12:13], v[12:13], 0, v[16:17]
	v_mov_b32_e32 v16, v17
	v_lshl_add_u64 v[4:5], v[4:5], 0, s[34:35]
	v_lshl_add_u64 v[6:7], s[30:31], 0, v[6:7]
	v_lshl_add_u64 v[8:9], v[8:9], 0, s[34:35]
	v_lshl_add_u64 v[10:11], s[30:31], 0, v[10:11]
	v_lshl_add_u64 v[12:13], s[30:31], 0, v[12:13]
	s_mov_b32 s58, 0
	s_mov_b32 s10, 0xaaaaaaaa
	s_mov_b32 s14, 0xcccccccc
	s_mov_b32 s34, 0xf000f
	s_mov_b32 s36, 0xf000f0
	s_mov_b32 s42, 0xf000f00
	s_mov_b32 s44, 0xf000f000
	s_mov_b32 s59, 0x4d00000
	s_mov_b32 s60, 0xd504000
	s_mov_b32 s61, 0xdd04000
	s_mov_b32 s62, 0xe504000
	s_mov_b32 s63, 0xed04000
	v_mul_u32_u24_e32 v27, 0x90, v27
	s_mov_b64 s[46:47], 0x4000
	s_mov_b64 s[48:49], 0x200
	s_mov_b64 s[50:51], 0x8000
	v_mov_b64_e32 v[18:19], v[16:17]
	v_mov_b32_e32 v28, v17
	s_branch .LBB0_496

.LBB0_496:
	s_and_b32 s54, s58, 1
	s_waitcnt lgkmcnt(0)
	s_barrier
	s_and_saveexec_b64 s[40:41], s[4:5]
	s_xor_b64 s[52:53], exec, s[40:41]
	s_cbranch_execz .LBB0_498
	s_mov_b32 s11, s10
	s_mov_b32 s15, s14
	s_mov_b32 s35, s34
	s_mov_b32 s37, s36
	s_mov_b32 s43, s42
	s_mov_b32 s45, s44
	s_mul_i32 s40, s54, 0xa000
	s_mul_i32 s41, s54, 0xa00
	s_add_i32 s41, s41, 0x14000
	v_add_u32_e32 v29, s40, v24
	v_add_u32_e32 v31, v23, v22
	v_mul_u32_u24_e32 v31, 0x90, v31
	v_mov_b32_e32 v30, s41
	v_add_u32_e32 v31, s41, v31
	ds_read_b128 v[44:47], v29 offset:48
	ds_read_b128 v[64:67], v29 offset:1328
	ds_read_b128 v[40:43], v29 offset:32
	ds_read_b128 v[112:115], v31 offset:0
	ds_read_b128 v[32:35], v29 offset:0
	ds_read_b128 v[120:123], v30 offset:2304
	ds_read_b128 v[48:51], v29 offset:64
	ds_read_b128 v[60:63], v29 offset:1312
	ds_read_b128 v[52:55], v29 offset:1280
	ds_read_b128 v[36:39], v29 offset:16
	ds_read_b128 v[68:71], v29 offset:1344
	ds_read_b128 v[56:59], v29 offset:1296
	s_cmp_eq_u32 s58, 0
	s_cbranch_scc1 .Lscan_tail_skip0
	v_add_f32_e32 v206, v144, v145
	v_add_f32_e32 v207, v146, v147
	v_cndmask_b32_e64 v208, v204, v205, s[10:11]
	v_cndmask_b32_e64 v209, v205, v204, s[10:11]
	v_cndmask_b32_e64 v210, v206, v207, s[10:11]
	v_cndmask_b32_e64 v211, v207, v206, s[10:11]
	v_add_f32_dpp v212, v209, v208 quad_perm:[1,0,3,2] row_mask:0xf bank_mask:0xf bound_ctrl:1
	s_nop 0
	v_add_f32_dpp v213, v211, v210 quad_perm:[1,0,3,2] row_mask:0xf bank_mask:0xf bound_ctrl:1
	v_cndmask_b32_e64 v214, v212, v213, s[14:15]
	v_cndmask_b32_e64 v215, v213, v212, s[14:15]
	s_nop 1
	v_add_f32_dpp v216, v215, v214 quad_perm:[2,3,0,1] row_mask:0xf bank_mask:0xf bound_ctrl:1
	s_nop 1
	v_add_f32_dpp v216, v216, v216 row_ror:8 row_mask:0xf bank_mask:0xf bound_ctrl:1
	s_nop 1
	v_add_f32_dpp v216, v216, v216 row_ror:4 row_mask:0xf bank_mask:0xf bound_ctrl:1
	v_cndmask_b32_e64 v28, v28, v216, s[44:45]
	v_add_co_u32_e32 v218, vcc, 0x4cfc000, v12
	s_nop 1
	v_addc_co_u32_e32 v219, vcc, 0, v13, vcc
	global_store_dword v[218:219], v28, off
.Lscan_tail_skip0:
	s_waitcnt lgkmcnt(7)
	v_pk_mul_f32 v[132:133], v[16:17], v[44:45]
	v_pk_mul_f32 v[134:135], v[16:17], v[64:65]
	v_pk_fma_f32 v[132:133], v[18:19], v[46:47], v[132:133]
	v_pk_fma_f32 v[134:135], v[18:19], v[66:67], v[134:135]
	v_pk_mul_f32 v[136:137], v[112:113], v[40:41] op_sel_hi:[0,1]
	v_add_f32_e32 v148, v132, v133
	v_add_f32_e32 v149, v134, v135
	v_pk_mul_f32 v[138:139], v[112:113], v[42:43] op_sel_hi:[0,1]
	v_add_f32_dpp v148, v148, v148 quad_perm:[1,0,3,2] row_mask:0xf bank_mask:0xf bound_ctrl:1
	v_add_f32_dpp v149, v149, v149 quad_perm:[1,0,3,2] row_mask:0xf bank_mask:0xf bound_ctrl:1
	v_pk_fma_f32 v[136:137], v[16:17], v[32:33], v[136:137]
	v_add_f32_dpp v148, v148, v148 quad_perm:[2,3,0,1] row_mask:0xf bank_mask:0xf bound_ctrl:1
	v_add_f32_dpp v149, v149, v149 quad_perm:[2,3,0,1] row_mask:0xf bank_mask:0xf bound_ctrl:1
	v_pk_fma_f32 v[138:139], v[18:19], v[34:35], v[138:139]
	v_add_f32_dpp v148, v148, v148 row_half_mirror row_mask:0xf bank_mask:0xf bound_ctrl:1
	v_add_f32_dpp v149, v149, v149 row_half_mirror row_mask:0xf bank_mask:0xf bound_ctrl:1
	ds_read_b128 v[84:87], v29 offset:2608
	ds_read_b128 v[104:107], v29 offset:3888
	ds_read_b128 v[80:83], v29 offset:2592
	ds_read_b128 v[72:75], v29 offset:2560
	ds_read_b128 v[88:91], v29 offset:2624
	ds_read_b128 v[100:103], v29 offset:3872
	ds_read_b128 v[92:95], v29 offset:3840
	ds_read_b128 v[76:79], v29 offset:2576
	ds_read_b128 v[108:111], v29 offset:3904
	ds_read_b128 v[96:99], v29 offset:3856
	s_waitcnt lgkmcnt(10)
	v_pk_mul_f32 v[140:141], v[112:113], v[60:61] op_sel:[1,0] op_sel_hi:[1,1]
	v_add_f32_dpp v148, v148, v148 row_mirror row_mask:0xf bank_mask:0xf bound_ctrl:1
	v_add_f32_dpp v149, v149, v149 row_mirror row_mask:0xf bank_mask:0xf bound_ctrl:1
	v_pk_mul_f32 v[142:143], v[112:113], v[62:63] op_sel:[1,0] op_sel_hi:[1,1]
	v_fmac_f32_e32 v149, v112, v120
	v_pk_fma_f32 v[16:17], v[48:49], v[148:149], v[136:137] op_sel_hi:[1,0,1]
	v_pk_fma_f32 v[18:19], v[50:51], v[148:149], v[138:139] op_sel_hi:[1,0,1]
	v_pk_fma_f32 v[140:141], v[16:17], v[52:53], v[140:141]
	v_pk_mul_f32 v[144:145], v[16:17], v[36:37]
	v_pk_fma_f32 v[142:143], v[18:19], v[54:55], v[142:143]
	v_pk_fma_f32 v[144:145], v[18:19], v[38:39], v[144:145]
	v_pk_fma_f32 v[16:17], v[68:69], v[148:149], v[140:141] op_sel:[0,1,0] op_sel_hi:[1,1,1]
	v_pk_fma_f32 v[18:19], v[70:71], v[148:149], v[142:143] op_sel:[0,1,0] op_sel_hi:[1,1,1]
	v_pk_mul_f32 v[146:147], v[16:17], v[56:57]
	v_pk_fma_f32 v[146:147], v[18:19], v[58:59], v[146:147]
	s_waitcnt lgkmcnt(6)
	v_pk_mul_f32 v[132:133], v[16:17], v[84:85]
	v_pk_mul_f32 v[134:135], v[16:17], v[104:105]
	v_add_f32_e32 v200, v144, v145
	v_pk_fma_f32 v[132:133], v[18:19], v[86:87], v[132:133]
	v_pk_fma_f32 v[134:135], v[18:19], v[106:107], v[134:135]
	v_add_f32_e32 v201, v146, v147
	v_pk_mul_f32 v[136:137], v[114:115], v[80:81] op_sel_hi:[0,1]
	v_add_f32_e32 v148, v132, v133
	v_add_f32_e32 v149, v134, v135
	v_pk_mul_f32 v[138:139], v[114:115], v[82:83] op_sel_hi:[0,1]
	v_add_f32_dpp v148, v148, v148 quad_perm:[1,0,3,2] row_mask:0xf bank_mask:0xf bound_ctrl:1
	v_add_f32_dpp v149, v149, v149 quad_perm:[1,0,3,2] row_mask:0xf bank_mask:0xf bound_ctrl:1
	v_pk_fma_f32 v[136:137], v[16:17], v[72:73], v[136:137]
	v_add_f32_dpp v148, v148, v148 quad_perm:[2,3,0,1] row_mask:0xf bank_mask:0xf bound_ctrl:1
	v_add_f32_dpp v149, v149, v149 quad_perm:[2,3,0,1] row_mask:0xf bank_mask:0xf bound_ctrl:1
	v_pk_fma_f32 v[138:139], v[18:19], v[74:75], v[138:139]
	v_add_f32_dpp v148, v148, v148 row_half_mirror row_mask:0xf bank_mask:0xf bound_ctrl:1
	v_add_f32_dpp v149, v149, v149 row_half_mirror row_mask:0xf bank_mask:0xf bound_ctrl:1
	ds_read_b128 v[172:175], v29 offset:5168
	ds_read_b128 v[192:195], v29 offset:6448
	ds_read_b128 v[168:171], v29 offset:5152
	ds_read_b128 v[116:119], v31 offset:16
	ds_read_b128 v[160:163], v29 offset:5120
	ds_read_b128 v[176:179], v29 offset:5184
	ds_read_b128 v[188:191], v29 offset:6432
	ds_read_b128 v[180:183], v29 offset:6400
	ds_read_b128 v[164:167], v29 offset:5136
	ds_read_b128 v[196:199], v29 offset:6464
	ds_read_b128 v[184:187], v29 offset:6416
	s_waitcnt lgkmcnt(11)
	v_pk_mul_f32 v[140:141], v[114:115], v[100:101] op_sel:[1,0] op_sel_hi:[1,1]
	v_add_f32_dpp v148, v148, v148 row_mirror row_mask:0xf bank_mask:0xf bound_ctrl:1
	v_add_f32_dpp v149, v149, v149 row_mirror row_mask:0xf bank_mask:0xf bound_ctrl:1
	v_pk_mul_f32 v[142:143], v[114:115], v[102:103] op_sel:[1,0] op_sel_hi:[1,1]
	v_fmac_f32_e32 v149, v114, v121
	v_pk_fma_f32 v[16:17], v[88:89], v[148:149], v[136:137] op_sel_hi:[1,0,1]
	v_pk_fma_f32 v[18:19], v[90:91], v[148:149], v[138:139] op_sel_hi:[1,0,1]
	v_pk_fma_f32 v[140:141], v[16:17], v[92:93], v[140:141]
	v_pk_mul_f32 v[144:145], v[16:17], v[76:77]
	v_pk_fma_f32 v[142:143], v[18:19], v[94:95], v[142:143]
	v_pk_fma_f32 v[144:145], v[18:19], v[78:79], v[144:145]
	v_pk_fma_f32 v[16:17], v[108:109], v[148:149], v[140:141] op_sel:[0,1,0] op_sel_hi:[1,1,1]
	v_pk_fma_f32 v[18:19], v[110:111], v[148:149], v[142:143] op_sel:[0,1,0] op_sel_hi:[1,1,1]
	v_pk_mul_f32 v[146:147], v[16:17], v[96:97]
	v_pk_fma_f32 v[146:147], v[18:19], v[98:99], v[146:147]
	s_waitcnt lgkmcnt(6)
	v_pk_mul_f32 v[132:133], v[16:17], v[172:173]
	v_pk_mul_f32 v[134:135], v[16:17], v[192:193]
	v_add_f32_e32 v202, v144, v145
	v_pk_fma_f32 v[132:133], v[18:19], v[174:175], v[132:133]
	v_pk_fma_f32 v[134:135], v[18:19], v[194:195], v[134:135]
	v_add_f32_e32 v203, v146, v147
	v_pk_mul_f32 v[136:137], v[116:117], v[168:169] op_sel_hi:[0,1]
	v_add_f32_e32 v148, v132, v133
	v_cndmask_b32_e64 v208, v200, v201, s[10:11]
	v_add_f32_e32 v149, v134, v135
	v_pk_mul_f32 v[138:139], v[116:117], v[170:171] op_sel_hi:[0,1]
	v_cndmask_b32_e64 v209, v201, v200, s[10:11]
	v_add_f32_dpp v148, v148, v148 quad_perm:[1,0,3,2] row_mask:0xf bank_mask:0xf bound_ctrl:1
	v_add_f32_dpp v149, v149, v149 quad_perm:[1,0,3,2] row_mask:0xf bank_mask:0xf bound_ctrl:1
	v_cndmask_b32_e64 v210, v202, v203, s[10:11]
	v_pk_fma_f32 v[136:137], v[16:17], v[160:161], v[136:137]
	v_add_f32_dpp v148, v148, v148 quad_perm:[2,3,0,1] row_mask:0xf bank_mask:0xf bound_ctrl:1
	v_cndmask_b32_e64 v211, v203, v202, s[10:11]
	v_add_f32_dpp v149, v149, v149 quad_perm:[2,3,0,1] row_mask:0xf bank_mask:0xf bound_ctrl:1
	v_pk_fma_f32 v[138:139], v[18:19], v[162:163], v[138:139]
	v_add_f32_dpp v212, v209, v208 quad_perm:[1,0,3,2] row_mask:0xf bank_mask:0xf bound_ctrl:1
	v_add_f32_dpp v148, v148, v148 row_half_mirror row_mask:0xf bank_mask:0xf bound_ctrl:1
	v_add_f32_dpp v149, v149, v149 row_half_mirror row_mask:0xf bank_mask:0xf bound_ctrl:1
	v_add_f32_dpp v213, v211, v210 quad_perm:[1,0,3,2] row_mask:0xf bank_mask:0xf bound_ctrl:1
	ds_read_b128 v[44:47], v29 offset:7728
	ds_read_b128 v[64:67], v29 offset:9008
	ds_read_b128 v[40:43], v29 offset:7712
	ds_read_b128 v[32:35], v29 offset:7680
	ds_read_b128 v[48:51], v29 offset:7744
	ds_read_b128 v[60:63], v29 offset:8992
	ds_read_b128 v[52:55], v29 offset:8960
	ds_read_b128 v[36:39], v29 offset:7696
	ds_read_b128 v[68:71], v29 offset:9024
	ds_read_b128 v[56:59], v29 offset:8976
	s_waitcnt lgkmcnt(10)
	v_pk_mul_f32 v[140:141], v[116:117], v[188:189] op_sel:[1,0] op_sel_hi:[1,1]
	v_cndmask_b32_e64 v214, v212, v213, s[14:15]
	v_add_f32_dpp v148, v148, v148 row_mirror row_mask:0xf bank_mask:0xf bound_ctrl:1
	v_add_f32_dpp v149, v149, v149 row_mirror row_mask:0xf bank_mask:0xf bound_ctrl:1
	v_cndmask_b32_e64 v215, v213, v212, s[14:15]
	v_pk_mul_f32 v[142:143], v[116:117], v[190:191] op_sel:[1,0] op_sel_hi:[1,1]
	v_fmac_f32_e32 v149, v116, v122
	v_add_f32_dpp v216, v215, v214 quad_perm:[2,3,0,1] row_mask:0xf bank_mask:0xf bound_ctrl:1
	v_pk_fma_f32 v[16:17], v[176:177], v[148:149], v[136:137] op_sel_hi:[1,0,1]
	v_pk_fma_f32 v[18:19], v[178:179], v[148:149], v[138:139] op_sel_hi:[1,0,1]
	v_add_f32_dpp v216, v216, v216 row_ror:8 row_mask:0xf bank_mask:0xf bound_ctrl:1
	v_pk_fma_f32 v[140:141], v[16:17], v[180:181], v[140:141]
	v_pk_mul_f32 v[144:145], v[16:17], v[164:165]
	v_add_f32_dpp v216, v216, v216 row_ror:4 row_mask:0xf bank_mask:0xf bound_ctrl:1
	v_pk_fma_f32 v[142:143], v[18:19], v[182:183], v[142:143]
	v_pk_fma_f32 v[144:145], v[18:19], v[166:167], v[144:145]
	v_cndmask_b32_e64 v28, v28, v216, s[34:35]
	v_pk_fma_f32 v[16:17], v[196:197], v[148:149], v[140:141] op_sel:[0,1,0] op_sel_hi:[1,1,1]
	v_pk_fma_f32 v[18:19], v[198:199], v[148:149], v[142:143] op_sel:[0,1,0] op_sel_hi:[1,1,1]
	v_pk_mul_f32 v[146:147], v[16:17], v[184:185]
	v_pk_fma_f32 v[146:147], v[18:19], v[186:187], v[146:147]
	s_waitcnt lgkmcnt(6)
	v_pk_mul_f32 v[132:133], v[16:17], v[44:45]
	v_pk_mul_f32 v[134:135], v[16:17], v[64:65]
	v_add_f32_e32 v204, v144, v145
	v_pk_fma_f32 v[132:133], v[18:19], v[46:47], v[132:133]
	v_pk_fma_f32 v[134:135], v[18:19], v[66:67], v[134:135]
	v_add_f32_e32 v205, v146, v147
	v_pk_mul_f32 v[136:137], v[118:119], v[40:41] op_sel_hi:[0,1]
	v_add_f32_e32 v148, v132, v133
	v_add_f32_e32 v149, v134, v135
	v_pk_mul_f32 v[138:139], v[118:119], v[42:43] op_sel_hi:[0,1]
	v_add_f32_dpp v148, v148, v148 quad_perm:[1,0,3,2] row_mask:0xf bank_mask:0xf bound_ctrl:1
	v_add_f32_dpp v149, v149, v149 quad_perm:[1,0,3,2] row_mask:0xf bank_mask:0xf bound_ctrl:1
	v_pk_fma_f32 v[136:137], v[16:17], v[32:33], v[136:137]
	v_add_f32_dpp v148, v148, v148 quad_perm:[2,3,0,1] row_mask:0xf bank_mask:0xf bound_ctrl:1
	v_add_f32_dpp v149, v149, v149 quad_perm:[2,3,0,1] row_mask:0xf bank_mask:0xf bound_ctrl:1
	v_pk_fma_f32 v[138:139], v[18:19], v[34:35], v[138:139]
	v_add_f32_dpp v148, v148, v148 row_half_mirror row_mask:0xf bank_mask:0xf bound_ctrl:1
	v_add_f32_dpp v149, v149, v149 row_half_mirror row_mask:0xf bank_mask:0xf bound_ctrl:1
	ds_read_b128 v[84:87], v29 offset:10288
	ds_read_b128 v[104:107], v29 offset:11568
	ds_read_b128 v[80:83], v29 offset:10272
	ds_read_b128 v[112:115], v31 offset:32
	ds_read_b128 v[72:75], v29 offset:10240
	ds_read_b128 v[124:127], v30 offset:2320
	ds_read_b128 v[88:91], v29 offset:10304
	ds_read_b128 v[100:103], v29 offset:11552
	ds_read_b128 v[92:95], v29 offset:11520
	ds_read_b128 v[76:79], v29 offset:10256
	ds_read_b128 v[108:111], v29 offset:11584
	ds_read_b128 v[96:99], v29 offset:11536
	s_waitcnt lgkmcnt(12)
	v_pk_mul_f32 v[140:141], v[118:119], v[60:61] op_sel:[1,0] op_sel_hi:[1,1]
	v_add_f32_dpp v148, v148, v148 row_mirror row_mask:0xf bank_mask:0xf bound_ctrl:1
	v_add_f32_dpp v149, v149, v149 row_mirror row_mask:0xf bank_mask:0xf bound_ctrl:1
	v_pk_mul_f32 v[142:143], v[118:119], v[62:63] op_sel:[1,0] op_sel_hi:[1,1]
	v_fmac_f32_e32 v149, v118, v123
	v_pk_fma_f32 v[16:17], v[48:49], v[148:149], v[136:137] op_sel_hi:[1,0,1]
	v_pk_fma_f32 v[18:19], v[50:51], v[148:149], v[138:139] op_sel_hi:[1,0,1]
	v_pk_fma_f32 v[140:141], v[16:17], v[52:53], v[140:141]
	v_pk_mul_f32 v[144:145], v[16:17], v[36:37]
	v_pk_fma_f32 v[142:143], v[18:19], v[54:55], v[142:143]
	v_pk_fma_f32 v[144:145], v[18:19], v[38:39], v[144:145]
	v_pk_fma_f32 v[16:17], v[68:69], v[148:149], v[140:141] op_sel:[0,1,0] op_sel_hi:[1,1,1]
	v_pk_fma_f32 v[18:19], v[70:71], v[148:149], v[142:143] op_sel:[0,1,0] op_sel_hi:[1,1,1]
	v_pk_mul_f32 v[146:147], v[16:17], v[56:57]
	v_pk_fma_f32 v[146:147], v[18:19], v[58:59], v[146:147]
	s_waitcnt lgkmcnt(7)
	v_pk_mul_f32 v[132:133], v[16:17], v[84:85]
	v_pk_mul_f32 v[134:135], v[16:17], v[104:105]
	v_add_f32_e32 v206, v144, v145
	v_pk_fma_f32 v[132:133], v[18:19], v[86:87], v[132:133]
	v_pk_fma_f32 v[134:135], v[18:19], v[106:107], v[134:135]
	v_add_f32_e32 v207, v146, v147
	v_pk_mul_f32 v[136:137], v[112:113], v[80:81] op_sel_hi:[0,1]
	v_add_f32_e32 v148, v132, v133
	v_cndmask_b32_e64 v208, v204, v205, s[10:11]
	v_add_f32_e32 v149, v134, v135
	v_pk_mul_f32 v[138:139], v[112:113], v[82:83] op_sel_hi:[0,1]
	v_cndmask_b32_e64 v209, v205, v204, s[10:11]
	v_add_f32_dpp v148, v148, v148 quad_perm:[1,0,3,2] row_mask:0xf bank_mask:0xf bound_ctrl:1
	v_add_f32_dpp v149, v149, v149 quad_perm:[1,0,3,2] row_mask:0xf bank_mask:0xf bound_ctrl:1
	v_cndmask_b32_e64 v210, v206, v207, s[10:11]
	v_pk_fma_f32 v[136:137], v[16:17], v[72:73], v[136:137]
	v_add_f32_dpp v148, v148, v148 quad_perm:[2,3,0,1] row_mask:0xf bank_mask:0xf bound_ctrl:1
	v_cndmask_b32_e64 v211, v207, v206, s[10:11]
	v_add_f32_dpp v149, v149, v149 quad_perm:[2,3,0,1] row_mask:0xf bank_mask:0xf bound_ctrl:1
	v_pk_fma_f32 v[138:139], v[18:19], v[74:75], v[138:139]
	v_add_f32_dpp v212, v209, v208 quad_perm:[1,0,3,2] row_mask:0xf bank_mask:0xf bound_ctrl:1
	v_add_f32_dpp v148, v148, v148 row_half_mirror row_mask:0xf bank_mask:0xf bound_ctrl:1
	v_add_f32_dpp v149, v149, v149 row_half_mirror row_mask:0xf bank_mask:0xf bound_ctrl:1
	v_add_f32_dpp v213, v211, v210 quad_perm:[1,0,3,2] row_mask:0xf bank_mask:0xf bound_ctrl:1
	ds_read_b128 v[172:175], v29 offset:12848
	ds_read_b128 v[192:195], v29 offset:14128
	ds_read_b128 v[168:171], v29 offset:12832
	ds_read_b128 v[160:163], v29 offset:12800
	ds_read_b128 v[176:179], v29 offset:12864
	ds_read_b128 v[188:191], v29 offset:14112
	ds_read_b128 v[180:183], v29 offset:14080
	ds_read_b128 v[164:167], v29 offset:12816
	ds_read_b128 v[196:199], v29 offset:14144
	ds_read_b128 v[184:187], v29 offset:14096
	s_waitcnt lgkmcnt(10)
	v_pk_mul_f32 v[140:141], v[112:113], v[100:101] op_sel:[1,0] op_sel_hi:[1,1]
	v_cndmask_b32_e64 v214, v212, v213, s[14:15]
	v_add_f32_dpp v148, v148, v148 row_mirror row_mask:0xf bank_mask:0xf bound_ctrl:1
	v_add_f32_dpp v149, v149, v149 row_mirror row_mask:0xf bank_mask:0xf bound_ctrl:1
	v_cndmask_b32_e64 v215, v213, v212, s[14:15]
	v_pk_mul_f32 v[142:143], v[112:113], v[102:103] op_sel:[1,0] op_sel_hi:[1,1]
	v_fmac_f32_e32 v149, v112, v124
	v_add_f32_dpp v216, v215, v214 quad_perm:[2,3,0,1] row_mask:0xf bank_mask:0xf bound_ctrl:1
	v_pk_fma_f32 v[16:17], v[88:89], v[148:149], v[136:137] op_sel_hi:[1,0,1]
	v_pk_fma_f32 v[18:19], v[90:91], v[148:149], v[138:139] op_sel_hi:[1,0,1]
	v_add_f32_dpp v216, v216, v216 row_ror:8 row_mask:0xf bank_mask:0xf bound_ctrl:1
	v_pk_fma_f32 v[140:141], v[16:17], v[92:93], v[140:141]
	v_pk_mul_f32 v[144:145], v[16:17], v[76:77]
	v_add_f32_dpp v216, v216, v216 row_ror:4 row_mask:0xf bank_mask:0xf bound_ctrl:1
	v_pk_fma_f32 v[142:143], v[18:19], v[94:95], v[142:143]
	v_pk_fma_f32 v[144:145], v[18:19], v[78:79], v[144:145]
	v_cndmask_b32_e64 v28, v28, v216, s[36:37]
	v_pk_fma_f32 v[16:17], v[108:109], v[148:149], v[140:141] op_sel:[0,1,0] op_sel_hi:[1,1,1]
	v_pk_fma_f32 v[18:19], v[110:111], v[148:149], v[142:143] op_sel:[0,1,0] op_sel_hi:[1,1,1]
	v_pk_mul_f32 v[146:147], v[16:17], v[96:97]
	v_pk_fma_f32 v[146:147], v[18:19], v[98:99], v[146:147]
	s_waitcnt lgkmcnt(6)
	v_pk_mul_f32 v[132:133], v[16:17], v[172:173]
	v_pk_mul_f32 v[134:135], v[16:17], v[192:193]
	v_add_f32_e32 v200, v144, v145
	v_pk_fma_f32 v[132:133], v[18:19], v[174:175], v[132:133]
	v_pk_fma_f32 v[134:135], v[18:19], v[194:195], v[134:135]
	v_add_f32_e32 v201, v146, v147
	v_pk_mul_f32 v[136:137], v[114:115], v[168:169] op_sel_hi:[0,1]
	v_add_f32_e32 v148, v132, v133
	v_add_f32_e32 v149, v134, v135
	v_pk_mul_f32 v[138:139], v[114:115], v[170:171] op_sel_hi:[0,1]
	v_add_f32_dpp v148, v148, v148 quad_perm:[1,0,3,2] row_mask:0xf bank_mask:0xf bound_ctrl:1
	v_add_f32_dpp v149, v149, v149 quad_perm:[1,0,3,2] row_mask:0xf bank_mask:0xf bound_ctrl:1
	v_pk_fma_f32 v[136:137], v[16:17], v[160:161], v[136:137]
	v_add_f32_dpp v148, v148, v148 quad_perm:[2,3,0,1] row_mask:0xf bank_mask:0xf bound_ctrl:1
	v_add_f32_dpp v149, v149, v149 quad_perm:[2,3,0,1] row_mask:0xf bank_mask:0xf bound_ctrl:1
	v_pk_fma_f32 v[138:139], v[18:19], v[162:163], v[138:139]
	v_add_f32_dpp v148, v148, v148 row_half_mirror row_mask:0xf bank_mask:0xf bound_ctrl:1
	v_add_f32_dpp v149, v149, v149 row_half_mirror row_mask:0xf bank_mask:0xf bound_ctrl:1
	ds_read_b128 v[44:47], v29 offset:15408
	ds_read_b128 v[64:67], v29 offset:16688
	ds_read_b128 v[40:43], v29 offset:15392
	ds_read_b128 v[116:119], v31 offset:48
	ds_read_b128 v[32:35], v29 offset:15360
	ds_read_b128 v[48:51], v29 offset:15424
	ds_read_b128 v[60:63], v29 offset:16672
	ds_read_b128 v[52:55], v29 offset:16640
	ds_read_b128 v[36:39], v29 offset:15376
	ds_read_b128 v[68:71], v29 offset:16704
	ds_read_b128 v[56:59], v29 offset:16656
	s_waitcnt lgkmcnt(11)
	v_pk_mul_f32 v[140:141], v[114:115], v[188:189] op_sel:[1,0] op_sel_hi:[1,1]
	v_add_f32_dpp v148, v148, v148 row_mirror row_mask:0xf bank_mask:0xf bound_ctrl:1
	v_add_f32_dpp v149, v149, v149 row_mirror row_mask:0xf bank_mask:0xf bound_ctrl:1
	v_pk_mul_f32 v[142:143], v[114:115], v[190:191] op_sel:[1,0] op_sel_hi:[1,1]
	v_fmac_f32_e32 v149, v114, v125
	v_pk_fma_f32 v[16:17], v[176:177], v[148:149], v[136:137] op_sel_hi:[1,0,1]
	v_pk_fma_f32 v[18:19], v[178:179], v[148:149], v[138:139] op_sel_hi:[1,0,1]
	v_pk_fma_f32 v[140:141], v[16:17], v[180:181], v[140:141]
	v_pk_mul_f32 v[144:145], v[16:17], v[164:165]
	v_pk_fma_f32 v[142:143], v[18:19], v[182:183], v[142:143]
	v_pk_fma_f32 v[144:145], v[18:19], v[166:167], v[144:145]
	v_pk_fma_f32 v[16:17], v[196:197], v[148:149], v[140:141] op_sel:[0,1,0] op_sel_hi:[1,1,1]
	v_pk_fma_f32 v[18:19], v[198:199], v[148:149], v[142:143] op_sel:[0,1,0] op_sel_hi:[1,1,1]
	v_pk_mul_f32 v[146:147], v[16:17], v[184:185]
	v_pk_fma_f32 v[146:147], v[18:19], v[186:187], v[146:147]
	s_waitcnt lgkmcnt(6)
	v_pk_mul_f32 v[132:133], v[16:17], v[44:45]
	v_pk_mul_f32 v[134:135], v[16:17], v[64:65]
	v_add_f32_e32 v202, v144, v145
	v_pk_fma_f32 v[132:133], v[18:19], v[46:47], v[132:133]
	v_pk_fma_f32 v[134:135], v[18:19], v[66:67], v[134:135]
	v_add_f32_e32 v203, v146, v147
	v_pk_mul_f32 v[136:137], v[116:117], v[40:41] op_sel_hi:[0,1]
	v_add_f32_e32 v148, v132, v133
	v_cndmask_b32_e64 v208, v200, v201, s[10:11]
	v_add_f32_e32 v149, v134, v135
	v_pk_mul_f32 v[138:139], v[116:117], v[42:43] op_sel_hi:[0,1]
	v_cndmask_b32_e64 v209, v201, v200, s[10:11]
	v_add_f32_dpp v148, v148, v148 quad_perm:[1,0,3,2] row_mask:0xf bank_mask:0xf bound_ctrl:1
	v_add_f32_dpp v149, v149, v149 quad_perm:[1,0,3,2] row_mask:0xf bank_mask:0xf bound_ctrl:1
	v_cndmask_b32_e64 v210, v202, v203, s[10:11]
	v_pk_fma_f32 v[136:137], v[16:17], v[32:33], v[136:137]
	v_add_f32_dpp v148, v148, v148 quad_perm:[2,3,0,1] row_mask:0xf bank_mask:0xf bound_ctrl:1
	v_cndmask_b32_e64 v211, v203, v202, s[10:11]
	v_add_f32_dpp v149, v149, v149 quad_perm:[2,3,0,1] row_mask:0xf bank_mask:0xf bound_ctrl:1
	v_pk_fma_f32 v[138:139], v[18:19], v[34:35], v[138:139]
	v_add_f32_dpp v212, v209, v208 quad_perm:[1,0,3,2] row_mask:0xf bank_mask:0xf bound_ctrl:1
	v_add_f32_dpp v148, v148, v148 row_half_mirror row_mask:0xf bank_mask:0xf bound_ctrl:1
	v_add_f32_dpp v149, v149, v149 row_half_mirror row_mask:0xf bank_mask:0xf bound_ctrl:1
	v_add_f32_dpp v213, v211, v210 quad_perm:[1,0,3,2] row_mask:0xf bank_mask:0xf bound_ctrl:1
	ds_read_b128 v[84:87], v29 offset:17968
	ds_read_b128 v[104:107], v29 offset:19248
	ds_read_b128 v[80:83], v29 offset:17952
	ds_read_b128 v[72:75], v29 offset:17920
	ds_read_b128 v[88:91], v29 offset:17984
	ds_read_b128 v[100:103], v29 offset:19232
	ds_read_b128 v[92:95], v29 offset:19200
	ds_read_b128 v[76:79], v29 offset:17936
	ds_read_b128 v[108:111], v29 offset:19264
	ds_read_b128 v[96:99], v29 offset:19216
	s_waitcnt lgkmcnt(10)
	v_pk_mul_f32 v[140:141], v[116:117], v[60:61] op_sel:[1,0] op_sel_hi:[1,1]
	v_cndmask_b32_e64 v214, v212, v213, s[14:15]
	v_add_f32_dpp v148, v148, v148 row_mirror row_mask:0xf bank_mask:0xf bound_ctrl:1
	v_add_f32_dpp v149, v149, v149 row_mirror row_mask:0xf bank_mask:0xf bound_ctrl:1
	v_cndmask_b32_e64 v215, v213, v212, s[14:15]
	v_pk_mul_f32 v[142:143], v[116:117], v[62:63] op_sel:[1,0] op_sel_hi:[1,1]
	v_fmac_f32_e32 v149, v116, v126
	v_add_f32_dpp v216, v215, v214 quad_perm:[2,3,0,1] row_mask:0xf bank_mask:0xf bound_ctrl:1
	v_pk_fma_f32 v[16:17], v[48:49], v[148:149], v[136:137] op_sel_hi:[1,0,1]
	v_pk_fma_f32 v[18:19], v[50:51], v[148:149], v[138:139] op_sel_hi:[1,0,1]
	v_add_f32_dpp v216, v216, v216 row_ror:8 row_mask:0xf bank_mask:0xf bound_ctrl:1
	v_pk_fma_f32 v[140:141], v[16:17], v[52:53], v[140:141]
	v_pk_mul_f32 v[144:145], v[16:17], v[36:37]
	v_add_f32_dpp v216, v216, v216 row_ror:4 row_mask:0xf bank_mask:0xf bound_ctrl:1
	v_pk_fma_f32 v[142:143], v[18:19], v[54:55], v[142:143]
	v_pk_fma_f32 v[144:145], v[18:19], v[38:39], v[144:145]
	v_cndmask_b32_e64 v28, v28, v216, s[42:43]
	v_pk_fma_f32 v[16:17], v[68:69], v[148:149], v[140:141] op_sel:[0,1,0] op_sel_hi:[1,1,1]
	v_pk_fma_f32 v[18:19], v[70:71], v[148:149], v[142:143] op_sel:[0,1,0] op_sel_hi:[1,1,1]
	v_pk_mul_f32 v[146:147], v[16:17], v[56:57]
	v_pk_fma_f32 v[146:147], v[18:19], v[58:59], v[146:147]
	s_waitcnt lgkmcnt(6)
	v_pk_mul_f32 v[132:133], v[16:17], v[84:85]
	v_pk_mul_f32 v[134:135], v[16:17], v[104:105]
	v_add_f32_e32 v204, v144, v145
	v_pk_fma_f32 v[132:133], v[18:19], v[86:87], v[132:133]
	v_pk_fma_f32 v[134:135], v[18:19], v[106:107], v[134:135]
	v_add_f32_e32 v205, v146, v147
	v_pk_mul_f32 v[136:137], v[118:119], v[80:81] op_sel_hi:[0,1]
	v_add_f32_e32 v148, v132, v133
	v_add_f32_e32 v149, v134, v135
	v_pk_mul_f32 v[138:139], v[118:119], v[82:83] op_sel_hi:[0,1]
	v_add_f32_dpp v148, v148, v148 quad_perm:[1,0,3,2] row_mask:0xf bank_mask:0xf bound_ctrl:1
	v_add_f32_dpp v149, v149, v149 quad_perm:[1,0,3,2] row_mask:0xf bank_mask:0xf bound_ctrl:1
	v_pk_fma_f32 v[136:137], v[16:17], v[72:73], v[136:137]
	v_add_f32_dpp v148, v148, v148 quad_perm:[2,3,0,1] row_mask:0xf bank_mask:0xf bound_ctrl:1
	v_add_f32_dpp v149, v149, v149 quad_perm:[2,3,0,1] row_mask:0xf bank_mask:0xf bound_ctrl:1
	v_pk_fma_f32 v[138:139], v[18:19], v[74:75], v[138:139]
	v_add_f32_dpp v148, v148, v148 row_half_mirror row_mask:0xf bank_mask:0xf bound_ctrl:1
	v_add_f32_dpp v149, v149, v149 row_half_mirror row_mask:0xf bank_mask:0xf bound_ctrl:1
	ds_read_b128 v[172:175], v29 offset:20528
	ds_read_b128 v[192:195], v29 offset:21808
	ds_read_b128 v[168:171], v29 offset:20512
	ds_read_b128 v[112:115], v31 offset:64
	ds_read_b128 v[160:163], v29 offset:20480
	ds_read_b128 v[120:123], v30 offset:2336
	ds_read_b128 v[176:179], v29 offset:20544
	ds_read_b128 v[188:191], v29 offset:21792
	ds_read_b128 v[180:183], v29 offset:21760
	ds_read_b128 v[164:167], v29 offset:20496
	ds_read_b128 v[196:199], v29 offset:21824
	ds_read_b128 v[184:187], v29 offset:21776
	s_waitcnt lgkmcnt(12)
	v_pk_mul_f32 v[140:141], v[118:119], v[100:101] op_sel:[1,0] op_sel_hi:[1,1]
	v_add_f32_dpp v148, v148, v148 row_mirror row_mask:0xf bank_mask:0xf bound_ctrl:1
	v_add_f32_dpp v149, v149, v149 row_mirror row_mask:0xf bank_mask:0xf bound_ctrl:1
	v_pk_mul_f32 v[142:143], v[118:119], v[102:103] op_sel:[1,0] op_sel_hi:[1,1]
	v_fmac_f32_e32 v149, v118, v127
	v_pk_fma_f32 v[16:17], v[88:89], v[148:149], v[136:137] op_sel_hi:[1,0,1]
	v_pk_fma_f32 v[18:19], v[90:91], v[148:149], v[138:139] op_sel_hi:[1,0,1]
	v_pk_fma_f32 v[140:141], v[16:17], v[92:93], v[140:141]
	v_pk_mul_f32 v[144:145], v[16:17], v[76:77]
	v_pk_fma_f32 v[142:143], v[18:19], v[94:95], v[142:143]
	v_pk_fma_f32 v[144:145], v[18:19], v[78:79], v[144:145]
	v_pk_fma_f32 v[16:17], v[108:109], v[148:149], v[140:141] op_sel:[0,1,0] op_sel_hi:[1,1,1]
	v_pk_fma_f32 v[18:19], v[110:111], v[148:149], v[142:143] op_sel:[0,1,0] op_sel_hi:[1,1,1]
	v_pk_mul_f32 v[146:147], v[16:17], v[96:97]
	v_pk_fma_f32 v[146:147], v[18:19], v[98:99], v[146:147]
	s_waitcnt lgkmcnt(7)
	v_pk_mul_f32 v[132:133], v[16:17], v[172:173]
	v_pk_mul_f32 v[134:135], v[16:17], v[192:193]
	v_add_f32_e32 v206, v144, v145
	v_pk_fma_f32 v[132:133], v[18:19], v[174:175], v[132:133]
	v_pk_fma_f32 v[134:135], v[18:19], v[194:195], v[134:135]
	v_add_f32_e32 v207, v146, v147
	v_pk_mul_f32 v[136:137], v[112:113], v[168:169] op_sel_hi:[0,1]
	v_add_f32_e32 v148, v132, v133
	v_cndmask_b32_e64 v208, v204, v205, s[10:11]
	v_add_f32_e32 v149, v134, v135
	v_pk_mul_f32 v[138:139], v[112:113], v[170:171] op_sel_hi:[0,1]
	v_cndmask_b32_e64 v209, v205, v204, s[10:11]
	v_add_f32_dpp v148, v148, v148 quad_perm:[1,0,3,2] row_mask:0xf bank_mask:0xf bound_ctrl:1
	v_add_f32_dpp v149, v149, v149 quad_perm:[1,0,3,2] row_mask:0xf bank_mask:0xf bound_ctrl:1
	v_cndmask_b32_e64 v210, v206, v207, s[10:11]
	v_pk_fma_f32 v[136:137], v[16:17], v[160:161], v[136:137]
	v_add_f32_dpp v148, v148, v148 quad_perm:[2,3,0,1] row_mask:0xf bank_mask:0xf bound_ctrl:1
	v_cndmask_b32_e64 v211, v207, v206, s[10:11]
	v_add_f32_dpp v149, v149, v149 quad_perm:[2,3,0,1] row_mask:0xf bank_mask:0xf bound_ctrl:1
	v_pk_fma_f32 v[138:139], v[18:19], v[162:163], v[138:139]
	v_add_f32_dpp v212, v209, v208 quad_perm:[1,0,3,2] row_mask:0xf bank_mask:0xf bound_ctrl:1
	v_add_f32_dpp v148, v148, v148 row_half_mirror row_mask:0xf bank_mask:0xf bound_ctrl:1
	v_add_f32_dpp v149, v149, v149 row_half_mirror row_mask:0xf bank_mask:0xf bound_ctrl:1
	v_add_f32_dpp v213, v211, v210 quad_perm:[1,0,3,2] row_mask:0xf bank_mask:0xf bound_ctrl:1
	ds_read_b128 v[44:47], v29 offset:23088
	ds_read_b128 v[64:67], v29 offset:24368
	ds_read_b128 v[40:43], v29 offset:23072
	ds_read_b128 v[32:35], v29 offset:23040
	ds_read_b128 v[48:51], v29 offset:23104
	ds_read_b128 v[60:63], v29 offset:24352
	ds_read_b128 v[52:55], v29 offset:24320
	ds_read_b128 v[36:39], v29 offset:23056
	ds_read_b128 v[68:71], v29 offset:24384
	ds_read_b128 v[56:59], v29 offset:24336
	s_waitcnt lgkmcnt(10)
	v_pk_mul_f32 v[140:141], v[112:113], v[188:189] op_sel:[1,0] op_sel_hi:[1,1]
	v_cndmask_b32_e64 v214, v212, v213, s[14:15]
	v_add_f32_dpp v148, v148, v148 row_mirror row_mask:0xf bank_mask:0xf bound_ctrl:1
	v_add_f32_dpp v149, v149, v149 row_mirror row_mask:0xf bank_mask:0xf bound_ctrl:1
	v_cndmask_b32_e64 v215, v213, v212, s[14:15]
	v_pk_mul_f32 v[142:143], v[112:113], v[190:191] op_sel:[1,0] op_sel_hi:[1,1]
	v_fmac_f32_e32 v149, v112, v120
	v_add_f32_dpp v216, v215, v214 quad_perm:[2,3,0,1] row_mask:0xf bank_mask:0xf bound_ctrl:1
	v_pk_fma_f32 v[16:17], v[176:177], v[148:149], v[136:137] op_sel_hi:[1,0,1]
	v_pk_fma_f32 v[18:19], v[178:179], v[148:149], v[138:139] op_sel_hi:[1,0,1]
	v_add_f32_dpp v216, v216, v216 row_ror:8 row_mask:0xf bank_mask:0xf bound_ctrl:1
	v_pk_fma_f32 v[140:141], v[16:17], v[180:181], v[140:141]
	v_pk_mul_f32 v[144:145], v[16:17], v[164:165]
	v_add_f32_dpp v216, v216, v216 row_ror:4 row_mask:0xf bank_mask:0xf bound_ctrl:1
	v_pk_fma_f32 v[142:143], v[18:19], v[182:183], v[142:143]
	v_pk_fma_f32 v[144:145], v[18:19], v[166:167], v[144:145]
	v_cndmask_b32_e64 v28, v28, v216, s[44:45]
	v_pk_fma_f32 v[16:17], v[196:197], v[148:149], v[140:141] op_sel:[0,1,0] op_sel_hi:[1,1,1]
	v_pk_fma_f32 v[18:19], v[198:199], v[148:149], v[142:143] op_sel:[0,1,0] op_sel_hi:[1,1,1]
	v_add_co_u32_e32 v218, vcc, s59, v12
	v_pk_mul_f32 v[146:147], v[16:17], v[184:185]
	v_pk_fma_f32 v[146:147], v[18:19], v[186:187], v[146:147]
	s_nop 1
	v_addc_co_u32_e32 v219, vcc, 0, v13, vcc
	global_store_dword v[218:219], v28, off
	s_waitcnt lgkmcnt(6)
	v_pk_mul_f32 v[132:133], v[16:17], v[44:45]
	v_pk_mul_f32 v[134:135], v[16:17], v[64:65]
	v_add_f32_e32 v200, v144, v145
	v_pk_fma_f32 v[132:133], v[18:19], v[46:47], v[132:133]
	v_pk_fma_f32 v[134:135], v[18:19], v[66:67], v[134:135]
	v_add_f32_e32 v201, v146, v147
	v_pk_mul_f32 v[136:137], v[114:115], v[40:41] op_sel_hi:[0,1]
	v_add_f32_e32 v148, v132, v133
	v_add_f32_e32 v149, v134, v135
	v_pk_mul_f32 v[138:139], v[114:115], v[42:43] op_sel_hi:[0,1]
	v_add_f32_dpp v148, v148, v148 quad_perm:[1,0,3,2] row_mask:0xf bank_mask:0xf bound_ctrl:1
	v_add_f32_dpp v149, v149, v149 quad_perm:[1,0,3,2] row_mask:0xf bank_mask:0xf bound_ctrl:1
	v_pk_fma_f32 v[136:137], v[16:17], v[32:33], v[136:137]
	v_add_f32_dpp v148, v148, v148 quad_perm:[2,3,0,1] row_mask:0xf bank_mask:0xf bound_ctrl:1
	v_add_f32_dpp v149, v149, v149 quad_perm:[2,3,0,1] row_mask:0xf bank_mask:0xf bound_ctrl:1
	v_pk_fma_f32 v[138:139], v[18:19], v[34:35], v[138:139]
	v_add_f32_dpp v148, v148, v148 row_half_mirror row_mask:0xf bank_mask:0xf bound_ctrl:1
	v_add_f32_dpp v149, v149, v149 row_half_mirror row_mask:0xf bank_mask:0xf bound_ctrl:1
	ds_read_b128 v[84:87], v29 offset:25648
	ds_read_b128 v[104:107], v29 offset:26928
	ds_read_b128 v[80:83], v29 offset:25632
	ds_read_b128 v[116:119], v31 offset:80
	ds_read_b128 v[72:75], v29 offset:25600
	ds_read_b128 v[88:91], v29 offset:25664
	ds_read_b128 v[100:103], v29 offset:26912
	ds_read_b128 v[92:95], v29 offset:26880
	ds_read_b128 v[76:79], v29 offset:25616
	ds_read_b128 v[108:111], v29 offset:26944
	ds_read_b128 v[96:99], v29 offset:26896
	s_waitcnt lgkmcnt(11)
	v_pk_mul_f32 v[140:141], v[114:115], v[60:61] op_sel:[1,0] op_sel_hi:[1,1]
	v_add_f32_dpp v148, v148, v148 row_mirror row_mask:0xf bank_mask:0xf bound_ctrl:1
	v_add_f32_dpp v149, v149, v149 row_mirror row_mask:0xf bank_mask:0xf bound_ctrl:1
	v_pk_mul_f32 v[142:143], v[114:115], v[62:63] op_sel:[1,0] op_sel_hi:[1,1]
	v_fmac_f32_e32 v149, v114, v121
	v_pk_fma_f32 v[16:17], v[48:49], v[148:149], v[136:137] op_sel_hi:[1,0,1]
	v_pk_fma_f32 v[18:19], v[50:51], v[148:149], v[138:139] op_sel_hi:[1,0,1]
	v_pk_fma_f32 v[140:141], v[16:17], v[52:53], v[140:141]
	v_pk_mul_f32 v[144:145], v[16:17], v[36:37]
	v_pk_fma_f32 v[142:143], v[18:19], v[54:55], v[142:143]
	v_pk_fma_f32 v[144:145], v[18:19], v[38:39], v[144:145]
	v_pk_fma_f32 v[16:17], v[68:69], v[148:149], v[140:141] op_sel:[0,1,0] op_sel_hi:[1,1,1]
	v_pk_fma_f32 v[18:19], v[70:71], v[148:149], v[142:143] op_sel:[0,1,0] op_sel_hi:[1,1,1]
	v_pk_mul_f32 v[146:147], v[16:17], v[56:57]
	v_pk_fma_f32 v[146:147], v[18:19], v[58:59], v[146:147]
	s_waitcnt lgkmcnt(6)
	v_pk_mul_f32 v[132:133], v[16:17], v[84:85]
	v_pk_mul_f32 v[134:135], v[16:17], v[104:105]
	v_add_f32_e32 v202, v144, v145
	v_pk_fma_f32 v[132:133], v[18:19], v[86:87], v[132:133]
	v_pk_fma_f32 v[134:135], v[18:19], v[106:107], v[134:135]
	v_add_f32_e32 v203, v146, v147
	v_pk_mul_f32 v[136:137], v[116:117], v[80:81] op_sel_hi:[0,1]
	v_add_f32_e32 v148, v132, v133
	v_cndmask_b32_e64 v208, v200, v201, s[10:11]
	v_add_f32_e32 v149, v134, v135
	v_pk_mul_f32 v[138:139], v[116:117], v[82:83] op_sel_hi:[0,1]
	v_cndmask_b32_e64 v209, v201, v200, s[10:11]
	v_add_f32_dpp v148, v148, v148 quad_perm:[1,0,3,2] row_mask:0xf bank_mask:0xf bound_ctrl:1
	v_add_f32_dpp v149, v149, v149 quad_perm:[1,0,3,2] row_mask:0xf bank_mask:0xf bound_ctrl:1
	v_cndmask_b32_e64 v210, v202, v203, s[10:11]
	v_pk_fma_f32 v[136:137], v[16:17], v[72:73], v[136:137]
	v_add_f32_dpp v148, v148, v148 quad_perm:[2,3,0,1] row_mask:0xf bank_mask:0xf bound_ctrl:1
	v_cndmask_b32_e64 v211, v203, v202, s[10:11]
	v_add_f32_dpp v149, v149, v149 quad_perm:[2,3,0,1] row_mask:0xf bank_mask:0xf bound_ctrl:1
	v_pk_fma_f32 v[138:139], v[18:19], v[74:75], v[138:139]
	v_add_f32_dpp v212, v209, v208 quad_perm:[1,0,3,2] row_mask:0xf bank_mask:0xf bound_ctrl:1
	v_add_f32_dpp v148, v148, v148 row_half_mirror row_mask:0xf bank_mask:0xf bound_ctrl:1
	v_add_f32_dpp v149, v149, v149 row_half_mirror row_mask:0xf bank_mask:0xf bound_ctrl:1
	v_add_f32_dpp v213, v211, v210 quad_perm:[1,0,3,2] row_mask:0xf bank_mask:0xf bound_ctrl:1
	ds_read_b128 v[172:175], v29 offset:28208
	ds_read_b128 v[192:195], v29 offset:29488
	ds_read_b128 v[168:171], v29 offset:28192
	ds_read_b128 v[160:163], v29 offset:28160
	ds_read_b128 v[176:179], v29 offset:28224
	ds_read_b128 v[188:191], v29 offset:29472
	ds_read_b128 v[180:183], v29 offset:29440
	ds_read_b128 v[164:167], v29 offset:28176
	ds_read_b128 v[196:199], v29 offset:29504
	ds_read_b128 v[184:187], v29 offset:29456
	s_waitcnt lgkmcnt(10)
	v_pk_mul_f32 v[140:141], v[116:117], v[100:101] op_sel:[1,0] op_sel_hi:[1,1]
	v_cndmask_b32_e64 v214, v212, v213, s[14:15]
	v_add_f32_dpp v148, v148, v148 row_mirror row_mask:0xf bank_mask:0xf bound_ctrl:1
	v_add_f32_dpp v149, v149, v149 row_mirror row_mask:0xf bank_mask:0xf bound_ctrl:1
	v_cndmask_b32_e64 v215, v213, v212, s[14:15]
	v_pk_mul_f32 v[142:143], v[116:117], v[102:103] op_sel:[1,0] op_sel_hi:[1,1]
	v_fmac_f32_e32 v149, v116, v122
	v_add_f32_dpp v216, v215, v214 quad_perm:[2,3,0,1] row_mask:0xf bank_mask:0xf bound_ctrl:1
	v_pk_fma_f32 v[16:17], v[88:89], v[148:149], v[136:137] op_sel_hi:[1,0,1]
	v_pk_fma_f32 v[18:19], v[90:91], v[148:149], v[138:139] op_sel_hi:[1,0,1]
	v_add_f32_dpp v216, v216, v216 row_ror:8 row_mask:0xf bank_mask:0xf bound_ctrl:1
	v_pk_fma_f32 v[140:141], v[16:17], v[92:93], v[140:141]
	v_pk_mul_f32 v[144:145], v[16:17], v[76:77]
	v_add_f32_dpp v216, v216, v216 row_ror:4 row_mask:0xf bank_mask:0xf bound_ctrl:1
	v_pk_fma_f32 v[142:143], v[18:19], v[94:95], v[142:143]
	v_pk_fma_f32 v[144:145], v[18:19], v[78:79], v[144:145]
	v_cndmask_b32_e64 v28, v28, v216, s[34:35]
	v_pk_fma_f32 v[16:17], v[108:109], v[148:149], v[140:141] op_sel:[0,1,0] op_sel_hi:[1,1,1]
	v_pk_fma_f32 v[18:19], v[110:111], v[148:149], v[142:143] op_sel:[0,1,0] op_sel_hi:[1,1,1]
	v_pk_mul_f32 v[146:147], v[16:17], v[96:97]
	v_pk_fma_f32 v[146:147], v[18:19], v[98:99], v[146:147]
	s_waitcnt lgkmcnt(6)
	v_pk_mul_f32 v[132:133], v[16:17], v[172:173]
	v_pk_mul_f32 v[134:135], v[16:17], v[192:193]
	v_add_f32_e32 v204, v144, v145
	v_pk_fma_f32 v[132:133], v[18:19], v[174:175], v[132:133]
	v_pk_fma_f32 v[134:135], v[18:19], v[194:195], v[134:135]
	v_add_f32_e32 v205, v146, v147
	v_pk_mul_f32 v[136:137], v[118:119], v[168:169] op_sel_hi:[0,1]
	v_add_f32_e32 v148, v132, v133
	v_add_f32_e32 v149, v134, v135
	v_pk_mul_f32 v[138:139], v[118:119], v[170:171] op_sel_hi:[0,1]
	v_add_f32_dpp v148, v148, v148 quad_perm:[1,0,3,2] row_mask:0xf bank_mask:0xf bound_ctrl:1
	v_add_f32_dpp v149, v149, v149 quad_perm:[1,0,3,2] row_mask:0xf bank_mask:0xf bound_ctrl:1
	v_pk_fma_f32 v[136:137], v[16:17], v[160:161], v[136:137]
	v_add_f32_dpp v148, v148, v148 quad_perm:[2,3,0,1] row_mask:0xf bank_mask:0xf bound_ctrl:1
	v_add_f32_dpp v149, v149, v149 quad_perm:[2,3,0,1] row_mask:0xf bank_mask:0xf bound_ctrl:1
	v_pk_fma_f32 v[138:139], v[18:19], v[162:163], v[138:139]
	v_add_f32_dpp v148, v148, v148 row_half_mirror row_mask:0xf bank_mask:0xf bound_ctrl:1
	v_add_f32_dpp v149, v149, v149 row_half_mirror row_mask:0xf bank_mask:0xf bound_ctrl:1
	ds_read_b128 v[44:47], v29 offset:30768
	ds_read_b128 v[64:67], v29 offset:32048
	ds_read_b128 v[40:43], v29 offset:30752
	ds_read_b128 v[112:115], v31 offset:96
	ds_read_b128 v[32:35], v29 offset:30720
	ds_read_b128 v[124:127], v30 offset:2352
	ds_read_b128 v[48:51], v29 offset:30784
	ds_read_b128 v[60:63], v29 offset:32032
	ds_read_b128 v[52:55], v29 offset:32000
	ds_read_b128 v[36:39], v29 offset:30736
	ds_read_b128 v[68:71], v29 offset:32064
	ds_read_b128 v[56:59], v29 offset:32016
	s_waitcnt lgkmcnt(12)
	v_pk_mul_f32 v[140:141], v[118:119], v[188:189] op_sel:[1,0] op_sel_hi:[1,1]
	v_add_f32_dpp v148, v148, v148 row_mirror row_mask:0xf bank_mask:0xf bound_ctrl:1
	v_add_f32_dpp v149, v149, v149 row_mirror row_mask:0xf bank_mask:0xf bound_ctrl:1
	v_pk_mul_f32 v[142:143], v[118:119], v[190:191] op_sel:[1,0] op_sel_hi:[1,1]
	v_fmac_f32_e32 v149, v118, v123
	v_pk_fma_f32 v[16:17], v[176:177], v[148:149], v[136:137] op_sel_hi:[1,0,1]
	v_pk_fma_f32 v[18:19], v[178:179], v[148:149], v[138:139] op_sel_hi:[1,0,1]
	v_pk_fma_f32 v[140:141], v[16:17], v[180:181], v[140:141]
	v_pk_mul_f32 v[144:145], v[16:17], v[164:165]
	v_pk_fma_f32 v[142:143], v[18:19], v[182:183], v[142:143]
	v_pk_fma_f32 v[144:145], v[18:19], v[166:167], v[144:145]
	v_pk_fma_f32 v[16:17], v[196:197], v[148:149], v[140:141] op_sel:[0,1,0] op_sel_hi:[1,1,1]
	v_pk_fma_f32 v[18:19], v[198:199], v[148:149], v[142:143] op_sel:[0,1,0] op_sel_hi:[1,1,1]
	v_pk_mul_f32 v[146:147], v[16:17], v[184:185]
	v_pk_fma_f32 v[146:147], v[18:19], v[186:187], v[146:147]
	s_waitcnt lgkmcnt(7)
	v_pk_mul_f32 v[132:133], v[16:17], v[44:45]
	v_pk_mul_f32 v[134:135], v[16:17], v[64:65]
	v_add_f32_e32 v206, v144, v145
	v_pk_fma_f32 v[132:133], v[18:19], v[46:47], v[132:133]
	v_pk_fma_f32 v[134:135], v[18:19], v[66:67], v[134:135]
	v_add_f32_e32 v207, v146, v147
	v_pk_mul_f32 v[136:137], v[112:113], v[40:41] op_sel_hi:[0,1]
	v_add_f32_e32 v148, v132, v133
	v_cndmask_b32_e64 v208, v204, v205, s[10:11]
	v_add_f32_e32 v149, v134, v135
	v_pk_mul_f32 v[138:139], v[112:113], v[42:43] op_sel_hi:[0,1]
	v_cndmask_b32_e64 v209, v205, v204, s[10:11]
	v_add_f32_dpp v148, v148, v148 quad_perm:[1,0,3,2] row_mask:0xf bank_mask:0xf bound_ctrl:1
	v_add_f32_dpp v149, v149, v149 quad_perm:[1,0,3,2] row_mask:0xf bank_mask:0xf bound_ctrl:1
	v_cndmask_b32_e64 v210, v206, v207, s[10:11]
	v_pk_fma_f32 v[136:137], v[16:17], v[32:33], v[136:137]
	v_add_f32_dpp v148, v148, v148 quad_perm:[2,3,0,1] row_mask:0xf bank_mask:0xf bound_ctrl:1
	v_cndmask_b32_e64 v211, v207, v206, s[10:11]
	v_add_f32_dpp v149, v149, v149 quad_perm:[2,3,0,1] row_mask:0xf bank_mask:0xf bound_ctrl:1
	v_pk_fma_f32 v[138:139], v[18:19], v[34:35], v[138:139]
	v_add_f32_dpp v212, v209, v208 quad_perm:[1,0,3,2] row_mask:0xf bank_mask:0xf bound_ctrl:1
	v_add_f32_dpp v148, v148, v148 row_half_mirror row_mask:0xf bank_mask:0xf bound_ctrl:1
	v_add_f32_dpp v149, v149, v149 row_half_mirror row_mask:0xf bank_mask:0xf bound_ctrl:1
	v_add_f32_dpp v213, v211, v210 quad_perm:[1,0,3,2] row_mask:0xf bank_mask:0xf bound_ctrl:1
	ds_read_b128 v[84:87], v29 offset:33328
	ds_read_b128 v[104:107], v29 offset:34608
	ds_read_b128 v[80:83], v29 offset:33312
	ds_read_b128 v[72:75], v29 offset:33280
	ds_read_b128 v[88:91], v29 offset:33344
	ds_read_b128 v[100:103], v29 offset:34592
	ds_read_b128 v[92:95], v29 offset:34560
	ds_read_b128 v[76:79], v29 offset:33296
	ds_read_b128 v[108:111], v29 offset:34624
	ds_read_b128 v[96:99], v29 offset:34576
	s_waitcnt lgkmcnt(10)
	v_pk_mul_f32 v[140:141], v[112:113], v[60:61] op_sel:[1,0] op_sel_hi:[1,1]
	v_cndmask_b32_e64 v214, v212, v213, s[14:15]
	v_add_f32_dpp v148, v148, v148 row_mirror row_mask:0xf bank_mask:0xf bound_ctrl:1
	v_add_f32_dpp v149, v149, v149 row_mirror row_mask:0xf bank_mask:0xf bound_ctrl:1
	v_cndmask_b32_e64 v215, v213, v212, s[14:15]
	v_pk_mul_f32 v[142:143], v[112:113], v[62:63] op_sel:[1,0] op_sel_hi:[1,1]
	v_fmac_f32_e32 v149, v112, v124
	v_add_f32_dpp v216, v215, v214 quad_perm:[2,3,0,1] row_mask:0xf bank_mask:0xf bound_ctrl:1
	v_pk_fma_f32 v[16:17], v[48:49], v[148:149], v[136:137] op_sel_hi:[1,0,1]
	v_pk_fma_f32 v[18:19], v[50:51], v[148:149], v[138:139] op_sel_hi:[1,0,1]
	v_add_f32_dpp v216, v216, v216 row_ror:8 row_mask:0xf bank_mask:0xf bound_ctrl:1
	v_pk_fma_f32 v[140:141], v[16:17], v[52:53], v[140:141]
	v_pk_mul_f32 v[144:145], v[16:17], v[36:37]
	v_add_f32_dpp v216, v216, v216 row_ror:4 row_mask:0xf bank_mask:0xf bound_ctrl:1
	v_pk_fma_f32 v[142:143], v[18:19], v[54:55], v[142:143]
	v_pk_fma_f32 v[144:145], v[18:19], v[38:39], v[144:145]
	v_cndmask_b32_e64 v28, v28, v216, s[36:37]
	v_pk_fma_f32 v[16:17], v[68:69], v[148:149], v[140:141] op_sel:[0,1,0] op_sel_hi:[1,1,1]
	v_pk_fma_f32 v[18:19], v[70:71], v[148:149], v[142:143] op_sel:[0,1,0] op_sel_hi:[1,1,1]
	v_pk_mul_f32 v[146:147], v[16:17], v[56:57]
	v_pk_fma_f32 v[146:147], v[18:19], v[58:59], v[146:147]
	s_waitcnt lgkmcnt(6)
	v_pk_mul_f32 v[132:133], v[16:17], v[84:85]
	v_pk_mul_f32 v[134:135], v[16:17], v[104:105]
	v_add_f32_e32 v200, v144, v145
	v_pk_fma_f32 v[132:133], v[18:19], v[86:87], v[132:133]
	v_pk_fma_f32 v[134:135], v[18:19], v[106:107], v[134:135]
	v_add_f32_e32 v201, v146, v147
	v_pk_mul_f32 v[136:137], v[114:115], v[80:81] op_sel_hi:[0,1]
	v_add_f32_e32 v148, v132, v133
	v_add_f32_e32 v149, v134, v135
	v_pk_mul_f32 v[138:139], v[114:115], v[82:83] op_sel_hi:[0,1]
	v_add_f32_dpp v148, v148, v148 quad_perm:[1,0,3,2] row_mask:0xf bank_mask:0xf bound_ctrl:1
	v_add_f32_dpp v149, v149, v149 quad_perm:[1,0,3,2] row_mask:0xf bank_mask:0xf bound_ctrl:1
	v_pk_fma_f32 v[136:137], v[16:17], v[72:73], v[136:137]
	v_add_f32_dpp v148, v148, v148 quad_perm:[2,3,0,1] row_mask:0xf bank_mask:0xf bound_ctrl:1
	v_add_f32_dpp v149, v149, v149 quad_perm:[2,3,0,1] row_mask:0xf bank_mask:0xf bound_ctrl:1
	v_pk_fma_f32 v[138:139], v[18:19], v[74:75], v[138:139]
	v_add_f32_dpp v148, v148, v148 row_half_mirror row_mask:0xf bank_mask:0xf bound_ctrl:1
	v_add_f32_dpp v149, v149, v149 row_half_mirror row_mask:0xf bank_mask:0xf bound_ctrl:1
	ds_read_b128 v[172:175], v29 offset:35888
	ds_read_b128 v[192:195], v29 offset:37168
	ds_read_b128 v[168:171], v29 offset:35872
	ds_read_b128 v[116:119], v31 offset:112
	ds_read_b128 v[160:163], v29 offset:35840
	ds_read_b128 v[176:179], v29 offset:35904
	ds_read_b128 v[188:191], v29 offset:37152
	ds_read_b128 v[180:183], v29 offset:37120
	ds_read_b128 v[164:167], v29 offset:35856
	ds_read_b128 v[196:199], v29 offset:37184
	ds_read_b128 v[184:187], v29 offset:37136
	s_waitcnt lgkmcnt(11)
	v_pk_mul_f32 v[140:141], v[114:115], v[100:101] op_sel:[1,0] op_sel_hi:[1,1]
	v_add_f32_dpp v148, v148, v148 row_mirror row_mask:0xf bank_mask:0xf bound_ctrl:1
	v_add_f32_dpp v149, v149, v149 row_mirror row_mask:0xf bank_mask:0xf bound_ctrl:1
	v_pk_mul_f32 v[142:143], v[114:115], v[102:103] op_sel:[1,0] op_sel_hi:[1,1]
	v_fmac_f32_e32 v149, v114, v125
	v_pk_fma_f32 v[16:17], v[88:89], v[148:149], v[136:137] op_sel_hi:[1,0,1]
	v_pk_fma_f32 v[18:19], v[90:91], v[148:149], v[138:139] op_sel_hi:[1,0,1]
	v_pk_fma_f32 v[140:141], v[16:17], v[92:93], v[140:141]
	v_pk_mul_f32 v[144:145], v[16:17], v[76:77]
	v_pk_fma_f32 v[142:143], v[18:19], v[94:95], v[142:143]
	v_pk_fma_f32 v[144:145], v[18:19], v[78:79], v[144:145]
	v_pk_fma_f32 v[16:17], v[108:109], v[148:149], v[140:141] op_sel:[0,1,0] op_sel_hi:[1,1,1]
	v_pk_fma_f32 v[18:19], v[110:111], v[148:149], v[142:143] op_sel:[0,1,0] op_sel_hi:[1,1,1]
	v_pk_mul_f32 v[146:147], v[16:17], v[96:97]
	v_pk_fma_f32 v[146:147], v[18:19], v[98:99], v[146:147]
	s_waitcnt lgkmcnt(6)
	v_pk_mul_f32 v[132:133], v[16:17], v[172:173]
	v_pk_mul_f32 v[134:135], v[16:17], v[192:193]
	v_add_f32_e32 v202, v144, v145
	v_pk_fma_f32 v[132:133], v[18:19], v[174:175], v[132:133]
	v_pk_fma_f32 v[134:135], v[18:19], v[194:195], v[134:135]
	v_add_f32_e32 v203, v146, v147
	v_pk_mul_f32 v[136:137], v[116:117], v[168:169] op_sel_hi:[0,1]
	v_add_f32_e32 v148, v132, v133
	v_cndmask_b32_e64 v208, v200, v201, s[10:11]
	v_add_f32_e32 v149, v134, v135
	v_pk_mul_f32 v[138:139], v[116:117], v[170:171] op_sel_hi:[0,1]
	v_cndmask_b32_e64 v209, v201, v200, s[10:11]
	v_add_f32_dpp v148, v148, v148 quad_perm:[1,0,3,2] row_mask:0xf bank_mask:0xf bound_ctrl:1
	v_add_f32_dpp v149, v149, v149 quad_perm:[1,0,3,2] row_mask:0xf bank_mask:0xf bound_ctrl:1
	v_cndmask_b32_e64 v210, v202, v203, s[10:11]
	v_pk_fma_f32 v[136:137], v[16:17], v[160:161], v[136:137]
	v_add_f32_dpp v148, v148, v148 quad_perm:[2,3,0,1] row_mask:0xf bank_mask:0xf bound_ctrl:1
	v_cndmask_b32_e64 v211, v203, v202, s[10:11]
	v_add_f32_dpp v149, v149, v149 quad_perm:[2,3,0,1] row_mask:0xf bank_mask:0xf bound_ctrl:1
	v_pk_fma_f32 v[138:139], v[18:19], v[162:163], v[138:139]
	v_add_f32_dpp v212, v209, v208 quad_perm:[1,0,3,2] row_mask:0xf bank_mask:0xf bound_ctrl:1
	v_add_f32_dpp v148, v148, v148 row_half_mirror row_mask:0xf bank_mask:0xf bound_ctrl:1
	v_add_f32_dpp v149, v149, v149 row_half_mirror row_mask:0xf bank_mask:0xf bound_ctrl:1
	v_add_f32_dpp v213, v211, v210 quad_perm:[1,0,3,2] row_mask:0xf bank_mask:0xf bound_ctrl:1
	ds_read_b128 v[44:47], v29 offset:38448
	ds_read_b128 v[64:67], v29 offset:39728
	ds_read_b128 v[40:43], v29 offset:38432
	ds_read_b128 v[32:35], v29 offset:38400
	ds_read_b128 v[48:51], v29 offset:38464
	ds_read_b128 v[60:63], v29 offset:39712
	ds_read_b128 v[52:55], v29 offset:39680
	ds_read_b128 v[36:39], v29 offset:38416
	ds_read_b128 v[68:71], v29 offset:39744
	ds_read_b128 v[56:59], v29 offset:39696
	s_waitcnt lgkmcnt(10)
	v_pk_mul_f32 v[140:141], v[116:117], v[188:189] op_sel:[1,0] op_sel_hi:[1,1]
	v_cndmask_b32_e64 v214, v212, v213, s[14:15]
	v_add_f32_dpp v148, v148, v148 row_mirror row_mask:0xf bank_mask:0xf bound_ctrl:1
	v_add_f32_dpp v149, v149, v149 row_mirror row_mask:0xf bank_mask:0xf bound_ctrl:1
	v_cndmask_b32_e64 v215, v213, v212, s[14:15]
	v_pk_mul_f32 v[142:143], v[116:117], v[190:191] op_sel:[1,0] op_sel_hi:[1,1]
	v_fmac_f32_e32 v149, v116, v126
	v_add_f32_dpp v216, v215, v214 quad_perm:[2,3,0,1] row_mask:0xf bank_mask:0xf bound_ctrl:1
	v_pk_fma_f32 v[16:17], v[176:177], v[148:149], v[136:137] op_sel_hi:[1,0,1]
	v_pk_fma_f32 v[18:19], v[178:179], v[148:149], v[138:139] op_sel_hi:[1,0,1]
	v_add_f32_dpp v216, v216, v216 row_ror:8 row_mask:0xf bank_mask:0xf bound_ctrl:1
	v_pk_fma_f32 v[140:141], v[16:17], v[180:181], v[140:141]
	v_pk_mul_f32 v[144:145], v[16:17], v[164:165]
	v_add_f32_dpp v216, v216, v216 row_ror:4 row_mask:0xf bank_mask:0xf bound_ctrl:1
	v_pk_fma_f32 v[142:143], v[18:19], v[182:183], v[142:143]
	v_pk_fma_f32 v[144:145], v[18:19], v[166:167], v[144:145]
	v_cndmask_b32_e64 v28, v28, v216, s[42:43]
	v_pk_fma_f32 v[16:17], v[196:197], v[148:149], v[140:141] op_sel:[0,1,0] op_sel_hi:[1,1,1]
	v_pk_fma_f32 v[18:19], v[198:199], v[148:149], v[142:143] op_sel:[0,1,0] op_sel_hi:[1,1,1]
	v_pk_mul_f32 v[146:147], v[16:17], v[184:185]
	v_pk_fma_f32 v[146:147], v[18:19], v[186:187], v[146:147]
	s_waitcnt lgkmcnt(6)
	v_pk_mul_f32 v[132:133], v[16:17], v[44:45]
	v_pk_mul_f32 v[134:135], v[16:17], v[64:65]
	v_add_f32_e32 v204, v144, v145
	v_pk_fma_f32 v[132:133], v[18:19], v[46:47], v[132:133]
	v_pk_fma_f32 v[134:135], v[18:19], v[66:67], v[134:135]
	v_add_f32_e32 v205, v146, v147
	v_pk_mul_f32 v[136:137], v[118:119], v[40:41] op_sel_hi:[0,1]
	v_add_f32_e32 v148, v132, v133
	v_add_f32_e32 v149, v134, v135
	v_pk_mul_f32 v[138:139], v[118:119], v[42:43] op_sel_hi:[0,1]
	v_add_f32_dpp v148, v148, v148 quad_perm:[1,0,3,2] row_mask:0xf bank_mask:0xf bound_ctrl:1
	v_add_f32_dpp v149, v149, v149 quad_perm:[1,0,3,2] row_mask:0xf bank_mask:0xf bound_ctrl:1
	v_pk_fma_f32 v[136:137], v[16:17], v[32:33], v[136:137]
	v_add_f32_dpp v148, v148, v148 quad_perm:[2,3,0,1] row_mask:0xf bank_mask:0xf bound_ctrl:1
	v_add_f32_dpp v149, v149, v149 quad_perm:[2,3,0,1] row_mask:0xf bank_mask:0xf bound_ctrl:1
	v_pk_fma_f32 v[138:139], v[18:19], v[34:35], v[138:139]
	v_add_f32_dpp v148, v148, v148 row_half_mirror row_mask:0xf bank_mask:0xf bound_ctrl:1
	v_add_f32_dpp v149, v149, v149 row_half_mirror row_mask:0xf bank_mask:0xf bound_ctrl:1
	s_waitcnt lgkmcnt(0)
	v_pk_mul_f32 v[140:141], v[118:119], v[60:61] op_sel:[1,0] op_sel_hi:[1,1]
	v_add_f32_dpp v148, v148, v148 row_mirror row_mask:0xf bank_mask:0xf bound_ctrl:1
	v_add_f32_dpp v149, v149, v149 row_mirror row_mask:0xf bank_mask:0xf bound_ctrl:1
	v_pk_mul_f32 v[142:143], v[118:119], v[62:63] op_sel:[1,0] op_sel_hi:[1,1]
	v_fmac_f32_e32 v149, v118, v127
	v_pk_fma_f32 v[16:17], v[48:49], v[148:149], v[136:137] op_sel_hi:[1,0,1]
	v_pk_fma_f32 v[18:19], v[50:51], v[148:149], v[138:139] op_sel_hi:[1,0,1]
	v_pk_fma_f32 v[140:141], v[16:17], v[52:53], v[140:141]
	v_pk_mul_f32 v[144:145], v[16:17], v[36:37]
	v_pk_fma_f32 v[142:143], v[18:19], v[54:55], v[142:143]
	v_pk_fma_f32 v[144:145], v[18:19], v[38:39], v[144:145]
	v_pk_fma_f32 v[16:17], v[68:69], v[148:149], v[140:141] op_sel:[0,1,0] op_sel_hi:[1,1,1]
	v_pk_fma_f32 v[18:19], v[70:71], v[148:149], v[142:143] op_sel:[0,1,0] op_sel_hi:[1,1,1]
	v_pk_mul_f32 v[146:147], v[16:17], v[56:57]
	v_pk_fma_f32 v[146:147], v[18:19], v[58:59], v[146:147]

.LBB0_504:
	s_andn2_saveexec_b64 s[54:55], s[54:55]
	s_cbranch_execz .LBB0_494
	v_lshl_add_u64 v[14:15], v[0:1], 0, s[28:29]
	global_load_dwordx2 v[14:15], v[14:15], off
	s_waitcnt vmcnt(0)
	v_lshlrev_b32_e32 v30, 16, v14
	v_and_b32_e32 v31, 0xffff0000, v14
	v_lshlrev_b32_e32 v32, 16, v15
	v_and_b32_e32 v33, 0xffff0000, v15
	v_add3_u32 v14, s11, v26, v27
	ds_write_b32 v14, v30
	ds_write_b32 v14, v31 offset:144
	ds_write_b32 v14, v32 offset:288
	ds_write_b32 v14, v33 offset:432
	s_branch .LBB0_494
